# attention: V^T fragment LDS reads hoisted to the top of the tile (own registers) so their latency overlaps QK and exp
# speedup vs baseline: 1.0065x; 1.0065x over previous
; __device__ __forceinline__ unsigned f2bf(float f) { unsigned u = __builtin_bit_cast(unsigned, f); return (u + 0x7fffu + ((u >> 16) & 1u)) >> 16; }
; __device__ __forceinline__ void phase_na_attn(const Fr& F) {
;     ...
;                         for (int ds = 0; ds < 2; ++ds) { const bf16x8 Kf = *(const bf16x8*)(Kl + (koff + 16 * st + l15) * KST + 32 * ds + 8 * lq);
;                             Sx[st] = __builtin_amdgcn_mfma_f32_16x16x32_bf16(Kf, Qf[ds], Sx[st], 0, 0, 0); } }
;                     float pv[2][4];
; #pragma unroll
;                     for (int st = 0; st < 2; ++st)
; #pragma unroll
;                         for (int reg = 0; reg < 4; ++reg) {
;                             if (nb) { const int bo = boff[st][reg]; pv[st][reg] = bo >= 0 ? __expf(Sx[st][reg] + rpbT[(rr - gi + 7) * 31 + bo]) : 0.f; }
;                             else pv[st][reg] = __expf(Sx[st][reg]); }
;                     u32x4 pw; pw.x = f2bf(pv[0][0]) | (f2bf(pv[0][1]) << 16); pw.y = f2bf(pv[0][2]) | (f2bf(pv[0][3]) << 16); pw.z = f2bf(pv[1][0]) | (f2bf(pv[1][1]) << 16); pw.w = f2bf(pv[1][2]) | (f2bf(pv[1][3]) << 16);
;                     lsum += ((lo_bf(pw.x) + hi_bf(pw.x)) + (lo_bf(pw.y) + hi_bf(pw.y))) + ((lo_bf(pw.z) + hi_bf(pw.z)) + (lo_bf(pw.w) + hi_bf(pw.w)));
;                     const bf16x8 Pb = __builtin_bit_cast(bf16x8, pw);
; #pragma unroll
;                     for (int dt = 0; dt < 4; ++dt) { const bf16* vp = Vl + (16 * dt + l15) * KST + koff + 4 * lq;
;                         u32x4 vw; const u32x2 v0 = *(const u32x2*)vp, v1 = *(const u32x2*)(vp + 16); vw.x = v0.x; vw.y = v0.y; vw.z = v1.x; vw.w = v1.y;
;                         O[dt] = __builtin_amdgcn_mfma_f32_16x16x32_bf16(__builtin_bit_cast(bf16x8, vw), Pb, O[dt], 0, 0, 0); }
.LBB0_1086:
	v_and_b32_sdwa v51, v55, v85 dst_sel:DWORD dst_unused:UNUSED_PAD src0_sel:WORD_1 src1_sel:DWORD
	v_add3_u32 v105, v55, v51, s74
	v_and_b32_sdwa v51, v48, v85 dst_sel:DWORD dst_unused:UNUSED_PAD src0_sel:WORD_1 src1_sel:DWORD
	v_and_b32_sdwa v55, v52, v85 dst_sel:DWORD dst_unused:UNUSED_PAD src0_sel:WORD_1 src1_sel:DWORD
	v_add3_u32 v48, v48, v51, s74
	v_add3_u32 v51, v52, v55, s74
	v_and_b32_e32 v108, 0xffff0000, v51
	v_and_b32_sdwa v51, v49, v85 dst_sel:DWORD dst_unused:UNUSED_PAD src0_sel:WORD_1 src1_sel:DWORD
	v_and_b32_sdwa v52, v53, v85 dst_sel:DWORD dst_unused:UNUSED_PAD src0_sel:WORD_1 src1_sel:DWORD
	v_add3_u32 v116, v49, v51, s74
	v_add3_u32 v118, v53, v52, s74
	v_and_b32_sdwa v49, v50, v85 dst_sel:DWORD dst_unused:UNUSED_PAD src0_sel:WORD_1 src1_sel:DWORD
	v_and_b32_sdwa v51, v54, v85 dst_sel:DWORD dst_unused:UNUSED_PAD src0_sel:WORD_1 src1_sel:DWORD
	v_add3_u32 v49, v50, v49, s74
	v_add3_u32 v50, v54, v51, s74
	v_and_b32_sdwa v104, v103, v85 dst_sel:DWORD dst_unused:UNUSED_PAD src0_sel:WORD_1 src1_sel:DWORD
	v_add3_u32 v103, v103, v104, s74
	v_and_b32_e32 v109, 0xffff0000, v48
	v_and_b32_e32 v113, 0xffff0000, v49
	v_and_b32_e32 v112, 0xffff0000, v50
	v_or_b32_sdwa v48, v108, v103 dst_sel:DWORD dst_unused:UNUSED_PAD src0_sel:DWORD src1_sel:WORD_1
	v_or_b32_sdwa v49, v112, v118 dst_sel:DWORD dst_unused:UNUSED_PAD src0_sel:DWORD src1_sel:WORD_1
	v_or_b32_sdwa v50, v109, v105 dst_sel:DWORD dst_unused:UNUSED_PAD src0_sel:DWORD src1_sel:WORD_1
	v_or_b32_sdwa v51, v113, v116 dst_sel:DWORD dst_unused:UNUSED_PAD src0_sel:DWORD src1_sel:WORD_1
	v_and_b32_e32 v110, 0xffff0000, v103
	v_and_b32_e32 v111, 0xffff0000, v105
	s_waitcnt lgkmcnt(0)
	v_mfma_f32_16x16x32_bf16 v[20:23], v[136:139], v[48:51], v[20:23]
	v_pk_add_f32 v[114:115], v[110:111], v[108:109]
	v_and_b32_e32 v117, 0xffff0000, v116
	v_and_b32_e32 v116, 0xffff0000, v118
	v_mfma_f32_16x16x32_bf16 v[16:19], v[140:143], v[48:51], v[16:19]
	v_add_f32_e64 v104, v116, v112
	v_add_f32_e64 v105, v117, v113
	s_add_i32 s85, s85, 32
	v_pk_add_f32 v[104:105], v[114:115], v[104:105]
	v_mfma_f32_16x16x32_bf16 v[12:15], v[144:147], v[48:51], v[12:15]
	v_add_f32_e32 v103, v104, v105
	v_add_f32_e32 v86, v86, v103
	s_cmp_lg_u32 s84, s85
	v_mfma_f32_16x16x32_bf16 v[8:11], v[148:151], v[48:51], v[8:11]
	s_cbranch_scc0 .LBB0_1134
.LBB0_1087:
	s_and_b64 s[24:25], s[54:55], exec
	s_cselect_b32 s86, s75, s85
	v_add_u32_e32 v48, s86, v61
	v_mad_u64_u32 v[108:109], s[24:25], v48, s73, v[66:67]
	ds_read_b128 v[48:51], v108
	ds_read_b128 v[52:55], v108 offset:64
	ds_read_b128 v[104:107], v108 offset:2304
	ds_read_b128 v[108:111], v108 offset:2368
	v_lshl_add_u32 v124, s86, 1, v82
	v_add_u32_e32 v120, 0x2000, v124
	v_add_u32_e32 v121, 0x2800, v124
	v_add_u32_e32 v122, 0x3000, v124
	v_add_u32_e32 v123, 0x3800, v124
	ds_read2_b64 v[136:139], v120 offset0:128 offset1:132
	ds_read2_b64 v[140:143], v121 offset0:160 offset1:164
	ds_read2_b64 v[144:147], v122 offset0:192 offset1:196
	ds_read2_b64 v[148:151], v123 offset0:224 offset1:228
	s_mov_b64 s[24:25], -1
	s_waitcnt lgkmcnt(7)
	v_mfma_f32_16x16x32_bf16 v[48:51], v[48:51], v[28:31], 0
	s_and_b64 vcc, exec, s[56:57]
	s_waitcnt lgkmcnt(5)
	v_mfma_f32_16x16x32_bf16 v[104:107], v[104:107], v[28:31], 0
	v_mfma_f32_16x16x32_bf16 v[52:55], v[52:55], v[24:27], v[48:51]
	s_waitcnt lgkmcnt(4)
	v_mfma_f32_16x16x32_bf16 v[48:51], v[108:111], v[24:27], v[104:107]
	s_cbranch_vccnz .Lattn_ctx1
	ds_read_b32 v112, v95 offset:50020
	ds_read_b32 v113, v96 offset:50020
	ds_read_b32 v114, v97 offset:50020
	ds_read_b32 v115, v98 offset:50020
	ds_read_b32 v116, v99 offset:50020
	ds_read_b32 v117, v100 offset:50020
	ds_read_b32 v118, v101 offset:50020
	ds_read_b32 v119, v102 offset:50020
	s_waitcnt lgkmcnt(0)
	v_add_f32_e32 v112, v52, v112
	v_add_f32_e32 v113, v53, v113
	v_add_f32_e32 v114, v54, v114
	v_add_f32_e32 v115, v55, v115
	v_add_f32_e32 v116, v48, v116
	v_add_f32_e32 v117, v49, v117
	v_add_f32_e32 v118, v50, v118
	v_add_f32_e32 v119, v51, v119
	v_mul_f32_e32 v112, 0x3fb8aa3b, v112
	v_mul_f32_e32 v113, 0x3fb8aa3b, v113
	v_mul_f32_e32 v114, 0x3fb8aa3b, v114
	v_mul_f32_e32 v115, 0x3fb8aa3b, v115
	v_mul_f32_e32 v116, 0x3fb8aa3b, v116
	v_mul_f32_e32 v117, 0x3fb8aa3b, v117
	v_mul_f32_e32 v118, 0x3fb8aa3b, v118
	v_mul_f32_e32 v119, 0x3fb8aa3b, v119
	v_exp_f32_e32 v112, v112
	v_exp_f32_e32 v113, v113
	v_exp_f32_e32 v114, v114
	v_exp_f32_e32 v115, v115
	v_exp_f32_e32 v116, v116
	v_exp_f32_e32 v117, v117
	v_exp_f32_e32 v118, v118
	v_exp_f32_e32 v119, v119
	v_cndmask_b32_e64 v103, 0, v112, s[8:9]
	v_cndmask_b32_e64 v52, 0, v113, s[10:11]
	v_cndmask_b32_e64 v53, 0, v114, s[12:13]
	v_cndmask_b32_e64 v54, 0, v115, s[14:15]
	v_cndmask_b32_e64 v55, 0, v116, s[16:17]
	v_cndmask_b32_e64 v48, 0, v117, s[18:19]
	v_cndmask_b32_e64 v49, 0, v118, s[20:21]
	v_cndmask_b32_e64 v50, 0, v119, s[22:23]
	s_branch .LBB0_1086

; __device__ __forceinline__ void phase_na_attn(const Fr& F) {
;     ...
;                         for (int ds = 0; ds < 2; ++ds) { const bf16x8 Kf = *(const bf16x8*)(Kl + (koff + 16 * st + l15) * KST + 32 * ds + 8 * lq);
;                             Sx[st] = __builtin_amdgcn_mfma_f32_16x16x32_bf16(Kf, Qf[ds], Sx[st], 0, 0, 0); } }
;                     float pv[2][4];
; #pragma unroll
;                     for (int st = 0; st < 2; ++st)
; #pragma unroll
;                         for (int reg = 0; reg < 4; ++reg) {
;                             if (nb) { const int bo = boff[st][reg]; pv[st][reg] = bo >= 0 ? __expf(Sx[st][reg] + rpbT[(rr - gi + 7) * 31 + bo]) : 0.f; }
;                             else pv[st][reg] = __expf(Sx[st][reg]); }
.LBB0_1148:
	s_and_b64 s[24:25], s[54:55], exec
	s_cselect_b32 s86, s75, s85
	v_add_u32_e32 v48, s86, v61
	v_mad_u64_u32 v[108:109], s[24:25], v48, s73, v[66:67]
	ds_read_b128 v[48:51], v108 offset:18432
	ds_read_b128 v[52:55], v108 offset:18496
	ds_read_b128 v[104:107], v108 offset:20736
	ds_read_b128 v[108:111], v108 offset:20800
	v_lshl_add_u32 v124, s86, 1, v82
	v_add_u32_e32 v120, 0x6800, v124
	v_add_u32_e32 v121, 0x7000, v124
	v_add_u32_e32 v122, 0x7800, v124
	v_add_u32_e32 v123, 0x8000, v124
	ds_read2_b64 v[136:139], v120 offset0:128 offset1:132
	ds_read2_b64 v[140:143], v121 offset0:160 offset1:164
	ds_read2_b64 v[144:147], v122 offset0:192 offset1:196
	ds_read2_b64 v[148:151], v123 offset0:224 offset1:228
	s_mov_b64 s[24:25], -1
	s_waitcnt lgkmcnt(7)
	v_mfma_f32_16x16x32_bf16 v[48:51], v[48:51], v[28:31], 0
	s_and_b64 vcc, exec, s[56:57]
	s_waitcnt lgkmcnt(5)
	v_mfma_f32_16x16x32_bf16 v[104:107], v[104:107], v[28:31], 0
	v_mfma_f32_16x16x32_bf16 v[52:55], v[52:55], v[24:27], v[48:51]
	s_waitcnt lgkmcnt(4)
	v_mfma_f32_16x16x32_bf16 v[48:51], v[108:111], v[24:27], v[104:107]
	s_cbranch_vccnz .Lattn_ctx0
	ds_read_b32 v112, v95 offset:50020
	ds_read_b32 v113, v96 offset:50020
	ds_read_b32 v114, v97 offset:50020
	ds_read_b32 v115, v98 offset:50020
	ds_read_b32 v116, v99 offset:50020
	ds_read_b32 v117, v100 offset:50020
	ds_read_b32 v118, v101 offset:50020
	ds_read_b32 v119, v102 offset:50020
	s_waitcnt lgkmcnt(0)
	v_add_f32_e32 v112, v52, v112
	v_add_f32_e32 v113, v53, v113
	v_add_f32_e32 v114, v54, v114
	v_add_f32_e32 v115, v55, v115
	v_add_f32_e32 v116, v48, v116
	v_add_f32_e32 v117, v49, v117
	v_add_f32_e32 v118, v50, v118
	v_add_f32_e32 v119, v51, v119
	v_mul_f32_e32 v112, 0x3fb8aa3b, v112
	v_mul_f32_e32 v113, 0x3fb8aa3b, v113
	v_mul_f32_e32 v114, 0x3fb8aa3b, v114
	v_mul_f32_e32 v115, 0x3fb8aa3b, v115
	v_mul_f32_e32 v116, 0x3fb8aa3b, v116
	v_mul_f32_e32 v117, 0x3fb8aa3b, v117
	v_mul_f32_e32 v118, 0x3fb8aa3b, v118
	v_mul_f32_e32 v119, 0x3fb8aa3b, v119
	v_exp_f32_e32 v112, v112
	v_exp_f32_e32 v113, v113
	v_exp_f32_e32 v114, v114
	v_exp_f32_e32 v115, v115
	v_exp_f32_e32 v116, v116
	v_exp_f32_e32 v117, v117
	v_exp_f32_e32 v118, v118
	v_exp_f32_e32 v119, v119
	v_cndmask_b32_e64 v103, 0, v112, s[8:9]
	v_cndmask_b32_e64 v52, 0, v113, s[10:11]
	v_cndmask_b32_e64 v53, 0, v114, s[12:13]
	v_cndmask_b32_e64 v54, 0, v115, s[14:15]
	v_cndmask_b32_e64 v55, 0, v116, s[16:17]
	v_cndmask_b32_e64 v48, 0, v117, s[18:19]
	v_cndmask_b32_e64 v49, 0, v118, s[20:21]
	v_cndmask_b32_e64 v50, 0, v119, s[22:23]
	s_branch .LBB0_1147
